# barrier spin loops keep two polls in flight
# baseline (speedup 1.0000x reference)
; __device__ __forceinline__ unsigned xb_ld(unsigned* p)              { return __hip_atomic_load(p, __ATOMIC_RELAXED, __HIP_MEMORY_SCOPE_AGENT); }
; #define XB_SPIN(cond, bar) do { unsigned _sp = 0; while (cond) { __builtin_amdgcn_s_sleep(1); \
;     if ((++_sp & 255u) == 0u) { if (xb_ld(&(bar)[XB_TMO])) break; if (_sp > XB_SPIN_CAP) { atomicAdd(&(bar)[XB_TMO], 1u); break; } } } } while (0)
; __device__ __forceinline__ void xcd_barrier(const XcdBarrier& b) {
;     ...
;             XB_SPIN(xb_ld(&bar[XB_XGEN(bx_)]) == gen, bar);
.LBB0_258:
	global_load_dword v3, v1, s[10:11] sc1
	s_add_i32 s22, s22, 1
	s_mov_b64 s[18:19], -1
	s_waitcnt vmcnt(1)
	v_cmp_ge_u32_e32 vcc, v3, v8
	s_orn2_b64 s[16:17], vcc, exec
	s_branch .LBB0_253

; __device__ __forceinline__ unsigned xb_ld(unsigned* p)              { return __hip_atomic_load(p, __ATOMIC_RELAXED, __HIP_MEMORY_SCOPE_AGENT); }
; #define XB_SPIN(cond, bar) do { unsigned _sp = 0; while (cond) { __builtin_amdgcn_s_sleep(1); \
;     if ((++_sp & 255u) == 0u) { if (xb_ld(&(bar)[XB_TMO])) break; if (_sp > XB_SPIN_CAP) { atomicAdd(&(bar)[XB_TMO], 1u); break; } } } } while (0)
; __device__ __forceinline__ void xcd_barrier(const XcdBarrier& b) {
;     ...
;             XB_SPIN(xb_ld(&bar[XB_XGEN(bx_)]) == gen, bar);
.LBB0_518:
	global_load_dword v4, v3, s[8:9] sc1
	s_add_i32 s20, s20, 1
	s_mov_b64 s[16:17], -1
	s_waitcnt vmcnt(1)
	v_cmp_ge_u32_e32 vcc, v4, v8
	s_orn2_b64 s[14:15], vcc, exec
	s_branch .LBB0_513

; __device__ __forceinline__ unsigned xb_ld(unsigned* p)              { return __hip_atomic_load(p, __ATOMIC_RELAXED, __HIP_MEMORY_SCOPE_AGENT); }
; #define XB_SPIN(cond, bar) do { unsigned _sp = 0; while (cond) { __builtin_amdgcn_s_sleep(1); \
;     if ((++_sp & 255u) == 0u) { if (xb_ld(&(bar)[XB_TMO])) break; if (_sp > XB_SPIN_CAP) { atomicAdd(&(bar)[XB_TMO], 1u); break; } } } } while (0)
; __device__ __forceinline__ void xcd_barrier(const XcdBarrier& b) {
;     ...
;             else XB_SPIN(xb_ld(&bar[XB_TOPGEN]) == tg, bar);
.LBB0_535:
	v_readlane_b32 s12, v253, 46
	v_readlane_b32 s13, v253, 47
	s_add_i32 s18, s18, 1
	s_mov_b64 s[14:15], -1
	s_nop 2
	global_load_dword v4, v3, s[12:13] sc1
	s_waitcnt vmcnt(1)
	v_cmp_ge_u32_e32 vcc, v4, v8
	s_orn2_b64 s[12:13], vcc, exec
	s_branch .LBB0_530
